# v47 + conv phase: loop-invariant weight loads hoisted out of the item loop (one global round trip per iteration instead of two)
# speedup vs baseline: 1.0018x; 1.0018x over previous
.LBB0_787:
	s_and_b64 vcc, exec, s[4:5]
	s_cbranch_vccz .LBB0_1200
	v_readlane_b32 s6, v254, 9
	s_mov_b64 s[4:5], 0
	v_mov_b32_e32 v0, v212
	s_mov_b32 s14, s6
	v_readlane_b32 s15, v254, 0
	s_mov_b32 s6, 0x200000
	s_nop 0
	v_lshl_add_u32 v20, s15, 9, v0
	v_readlane_b32 s7, v254, 10
	v_cmp_gt_i32_e32 vcc, s6, v20
	s_and_saveexec_b64 s[6:7], vcc
	s_movk_i32 s34, 0x1000
	s_mov_b64 s[36:37], 0x1000
	v_readlane_b32 s56, v255, 31
	s_cbranch_execz .LBB0_791
	s_add_u32 s4, s94, s4
	s_addc_u32 s5, s95, s5
	s_add_u32 s8, s4, 0xe000000
	s_addc_u32 s9, s5, 0
	s_ashr_i32 s10, s56, 1
	v_readlane_b32 s16, v254, 13
	s_mul_hi_i32 s11, s10, 0x1800
	s_mulk_i32 s10, 0x1800
	v_readlane_b32 s30, v254, 27
	v_readlane_b32 s31, v254, 28
	s_add_u32 s10, s30, s10
	s_addc_u32 s11, s31, s11
	v_readlane_b32 s17, v254, 14
	s_add_u32 s12, s4, 0x3000000
	v_lshlrev_b32_e32 v0, 3, v0
	s_addc_u32 s13, s5, 0
	s_lshl_b32 s16, s14, 9
	v_lshl_add_u32 v21, s15, 12, v0
	s_lshl_b32 s17, s14, 12
	s_mov_b64 s[14:15], 0
	v_readlane_b32 s18, v254, 15
	v_readlane_b32 s19, v254, 16
	v_readlane_b32 s20, v254, 17
	v_readlane_b32 s21, v254, 18
	v_readlane_b32 s22, v254, 19
	v_readlane_b32 s23, v254, 20
	v_readlane_b32 s24, v254, 21
	v_readlane_b32 s25, v254, 22
	v_readlane_b32 s26, v254, 23
	v_readlane_b32 s27, v254, 24
	v_readlane_b32 s28, v254, 25
	v_readlane_b32 s29, v254, 26
	v_and_b32_e32 v104, 0x1f8, v21
	v_lshlrev_b32_e32 v104, 2, v104
	v_add_u32_e32 v105, 0x1000, v104
	global_load_dwordx4 v[80:83], v104, s[10:11] offset:16
	global_load_dwordx4 v[84:87], v104, s[10:11]
	global_load_dwordx4 v[88:91], v104, s[10:11] offset:2064
	global_load_dwordx4 v[92:95], v104, s[10:11] offset:2048
	global_load_dwordx4 v[96:99], v105, s[10:11]
	global_load_dwordx4 v[100:103], v105, s[10:11] offset:16
	s_waitcnt vmcnt(0)
.LBB0_790:
	v_ashrrev_i32_e32 v18, 6, v20
	v_and_b32_e32 v22, 0xfff, v18
	v_mov_b64_e32 v[2:3], s[8:9]
	v_mad_i64_i32 v[14:15], s[4:5], v18, s50, v[2:3]
	v_cmp_eq_u32_e32 vcc, 0, v22
	v_and_b32_e32 v34, 0x1f8, v21
	v_cmp_lt_u32_e64 s[4:5], 1, v22
	v_cndmask_b32_e64 v17, -1, 0, vcc
	v_cndmask_b32_e64 v16, v225, 0, vcc
	v_lshlrev_b32_e32 v0, 1, v34
	v_lshl_add_u64 v[16:17], v[14:15], 0, v[16:17]
	v_cndmask_b32_e64 v23, 0, -1, s[4:5]
	v_cndmask_b32_e64 v22, 0, v226, s[4:5]
	v_lshl_add_u64 v[2:3], v[14:15], 0, v[0:1]
	v_lshl_add_u64 v[14:15], v[14:15], 0, v[22:23]
	v_lshl_add_u64 v[16:17], v[16:17], 0, v[0:1]
	global_load_dwordx4 v[6:9], v[2:3], off
	global_load_dwordx4 v[10:13], v[2:3], off offset:1024
	s_nop 0
	global_load_dwordx4 v[2:5], v[2:3], off offset:2048
	s_nop 0
	global_load_dwordx4 v[22:25], v[16:17], off offset:1024
	global_load_dwordx4 v[26:29], v[16:17], off offset:2048
	v_lshl_add_u64 v[14:15], v[14:15], 0, v[0:1]
	global_load_dwordx4 v[30:33], v[14:15], off offset:1024
	s_nop 0
	global_load_dwordx4 v[14:17], v[14:15], off offset:2048
	v_lshlrev_b32_e32 v38, 2, v34
	v_mov_b32_e32 v39, v1
	v_lshl_add_u64 v[42:43], s[10:11], 0, v[38:39]
	v_lshl_add_u64 v[46:47], v[42:43], 0, s[36:37]
	v_ashrrev_i32_e32 v19, 31, v18
	v_add_u32_e32 v20, s16, v20
	v_add_u32_e32 v21, s17, v21
	s_waitcnt vmcnt(6)
	v_lshlrev_b32_e32 v63, 16, v6
	v_and_b32_e32 v6, 0xffff0000, v6
	s_waitcnt vmcnt(3)
	v_cndmask_b32_e64 v50, v22, 0, vcc
	v_cndmask_b32_e64 v54, v23, 0, vcc
	v_cndmask_b32_e64 v55, v24, 0, vcc
	v_cndmask_b32_e64 v56, v25, 0, vcc
	v_add_co_u32_e32 v42, vcc, s34, v42
	s_waitcnt vmcnt(1)
	v_cndmask_b32_e64 v57, 0, v30, s[4:5]
	v_cndmask_b32_e64 v58, 0, v31, s[4:5]
	v_cndmask_b32_e64 v59, 0, v32, s[4:5]
	v_cndmask_b32_e64 v60, 0, v33, s[4:5]
	v_mov_b64_e32 v[22:23], v[80:81]
	v_mov_b64_e32 v[24:25], v[82:83]
	v_mov_b64_e32 v[30:31], v[84:85]
	v_mov_b64_e32 v[32:33], v[86:87]
	v_mov_b64_e32 v[34:35], v[88:89]
	v_mov_b64_e32 v[36:37], v[90:91]
	s_nop 0
	v_mov_b64_e32 v[38:39], v[92:93]
	v_mov_b64_e32 v[40:41], v[94:95]
	v_addc_co_u32_e32 v43, vcc, 0, v43, vcc
	v_mov_b64_e32 v[42:43], v[96:97]
	v_mov_b64_e32 v[44:45], v[98:99]
	s_nop 0
	v_mov_b64_e32 v[46:47], v[100:101]
	v_mov_b64_e32 v[48:49], v[102:103]
	v_and_b32_e32 v51, 0xffff0000, v26
	v_and_b32_e32 v52, 0xffff0000, v50
	v_mul_f32_e32 v61, v51, v52
	s_waitcnt vmcnt(0)
	v_lshlrev_b32_e32 v51, 16, v14
	v_lshlrev_b32_e32 v52, 16, v57
	v_mul_f32_e32 v62, v51, v52
	v_lshlrev_b32_e32 v51, 16, v10
	v_lshlrev_b32_e32 v50, 16, v50
	v_lshlrev_b32_e32 v53, 16, v2
	v_lshlrev_b32_e32 v52, 16, v26
	v_pk_mul_f32 v[50:51], v[50:51], v[52:53]
	s_mov_b32 s4, 0x1fffff
	v_cmp_lt_i32_e32 vcc, s4, v20
	s_or_b64 s[14:15], vcc, s[14:15]
	s_waitcnt vmcnt(2)
	v_mov_b32_e32 v52, v38
	s_waitcnt vmcnt(1)
	v_mov_b32_e32 v53, v42
	v_pk_mul_f32 v[50:51], v[50:51], v[52:53]
	v_and_b32_e32 v53, 0xffff0000, v2
	v_fma_f32 v26, v30, v62, v50
	v_add_f32_e32 v26, v26, v51
	v_and_b32_e32 v51, 0xffff0000, v10
	v_and_b32_e32 v50, 0xffff0000, v57
	v_and_b32_e32 v52, 0xffff0000, v14
	v_pk_mul_f32 v[50:51], v[50:51], v[52:53]
	v_mov_b32_e32 v42, v31
	v_pk_mul_f32 v[30:31], v[42:43], v[50:51]
	v_mul_f32_e32 v38, v26, v63
	v_fma_f32 v2, v61, v39, v30
	v_add_f32_e32 v2, v2, v31
	v_mul_f32_e32 v10, v2, v6
	v_lshlrev_b32_e32 v2, 16, v27
	v_lshlrev_b32_e32 v6, 16, v54
	v_mul_f32_e32 v2, v2, v6
	v_and_b32_e32 v6, 0xffff0000, v27
	v_lshlrev_b32_e32 v27, 16, v11
	v_lshlrev_b32_e32 v26, 16, v58
	v_lshlrev_b32_e32 v31, 16, v3
	v_lshlrev_b32_e32 v30, 16, v15
	v_pk_mul_f32 v[26:27], v[26:27], v[30:31]
	v_mov_b32_e32 v30, v32
	v_mov_b32_e32 v31, v44
	v_pk_mul_f32 v[26:27], v[26:27], v[30:31]
	v_and_b32_e32 v14, 0xffff0000, v54
	v_fma_f32 v2, v2, v40, v26
	v_mul_f32_e32 v14, v6, v14
	v_lshlrev_b32_e32 v6, 16, v7
	v_add_f32_e32 v2, v2, v27
	v_mul_f32_e32 v26, v2, v6
	v_and_b32_e32 v27, 0xffff0000, v7
	v_and_b32_e32 v7, 0xffff0000, v11
	v_and_b32_e32 v6, 0xffff0000, v58
	v_and_b32_e32 v3, 0xffff0000, v3
	v_and_b32_e32 v2, 0xffff0000, v15
	v_pk_mul_f32 v[2:3], v[6:7], v[2:3]
	v_mov_b32_e32 v44, v33
	v_pk_mul_f32 v[2:3], v[2:3], v[44:45]
	v_lshlrev_b32_e32 v7, 16, v4
	v_fma_f32 v2, v14, v41, v2
	v_add_f32_e32 v2, v2, v3
	v_mul_f32_e32 v11, v2, v27
	v_lshlrev_b32_e32 v2, 16, v28
	v_lshlrev_b32_e32 v3, 16, v55
	v_mul_f32_e32 v14, v2, v3
	v_and_b32_e32 v2, 0xffff0000, v28
	v_and_b32_e32 v3, 0xffff0000, v55
	v_mul_f32_e32 v15, v2, v3
	v_lshlrev_b32_e32 v3, 16, v12
	v_lshlrev_b32_e32 v2, 16, v59
	v_lshlrev_b32_e32 v6, 16, v16
	v_pk_mul_f32 v[2:3], v[2:3], v[6:7]
	v_mov_b32_e32 v6, v22
	s_waitcnt vmcnt(0)
	v_mov_b32_e32 v7, v46
	v_pk_mul_f32 v[2:3], v[2:3], v[6:7]
	v_lshlrev_b32_e32 v27, 16, v8
	v_fma_f32 v2, v14, v34, v2
	v_add_f32_e32 v2, v2, v3
	v_mul_f32_e32 v14, v2, v27
	v_and_b32_e32 v3, 0xffff0000, v12
	v_and_b32_e32 v2, 0xffff0000, v59
	v_and_b32_e32 v7, 0xffff0000, v4
	v_and_b32_e32 v6, 0xffff0000, v16
	v_pk_mul_f32 v[2:3], v[2:3], v[6:7]
	v_mov_b32_e32 v46, v23
	v_pk_mul_f32 v[2:3], v[2:3], v[46:47]
	v_and_b32_e32 v8, 0xffff0000, v8
	v_fma_f32 v2, v15, v35, v2
	v_add_f32_e32 v2, v2, v3
	v_mul_f32_e32 v8, v2, v8
	v_lshlrev_b32_e32 v2, 16, v29
	v_lshlrev_b32_e32 v3, 16, v56
	v_mul_f32_e32 v4, v2, v3
	v_and_b32_e32 v2, 0xffff0000, v29
	v_and_b32_e32 v3, 0xffff0000, v56
	v_mul_f32_e32 v12, v2, v3
	v_lshlrev_b32_e32 v3, 16, v13
	v_lshlrev_b32_e32 v2, 16, v60
	v_lshlrev_b32_e32 v7, 16, v5
	v_lshlrev_b32_e32 v6, 16, v17
	v_pk_mul_f32 v[2:3], v[2:3], v[6:7]
	v_mov_b32_e32 v6, v24
	v_mov_b32_e32 v7, v48
	v_pk_mul_f32 v[2:3], v[2:3], v[6:7]
	v_lshlrev_b32_e32 v15, 16, v9
	v_fma_f32 v2, v4, v36, v2
	v_add_f32_e32 v2, v2, v3
	v_mul_f32_e32 v6, v2, v15
	v_and_b32_e32 v3, 0xffff0000, v13
	v_and_b32_e32 v2, 0xffff0000, v60
	v_and_b32_e32 v5, 0xffff0000, v5
	v_and_b32_e32 v4, 0xffff0000, v17
	v_pk_mul_f32 v[2:3], v[2:3], v[4:5]
	v_mov_b32_e32 v48, v25
	v_pk_mul_f32 v[2:3], v[2:3], v[48:49]
	v_and_b32_e32 v7, 0xffff0000, v9
	v_fma_f32 v2, v12, v37, v2
	v_add_f32_e32 v2, v2, v3
	v_mul_f32_e32 v5, v2, v7
	v_cvt_pk_bf16_f32 v2, v38, v10
	v_cvt_pk_bf16_f32 v3, v26, v11
	v_cvt_pk_bf16_f32 v4, v14, v8
	v_cvt_pk_bf16_f32 v5, v6, v5
	v_lshlrev_b64 v[6:7], 11, v[18:19]
	v_lshl_add_u64 v[6:7], s[12:13], 0, v[6:7]
	v_lshl_add_u64 v[6:7], v[6:7], 0, v[0:1]
	global_store_dwordx4 v[6:7], v[2:5], off
	s_andn2_b64 exec, exec, s[14:15]
	s_cbranch_execnz .LBB0_790
